# P9 up-projection epilogue: waits for the sample-only conditional loads moved inside their branch, so non-sample tiles no longer drain their stores 12x per tile (on top of g2 rewrite)
# speedup vs baseline: 1.0226x; 1.0036x over previous
.LBB0_2312:
	v_mov_b32_e32 v150, 0
	v_mov_b32_e32 v151, 0
	v_mov_b32_e32 v152, 0
	v_mov_b32_e32 v153, 0
	v_mov_b32_e32 v184, 0
	v_mov_b32_e32 v185, 0
	v_mov_b32_e32 v186, 0
	v_mov_b32_e32 v182, 0
	v_or_b32_e32 v158, 16, v194
	v_mov_b32_dpp v150, v134 row_ror:1 row_mask:0xf bank_mask:0xf
	v_mov_b32_dpp v151, v135 row_ror:1 row_mask:0xf bank_mask:0xf
	v_mov_b32_dpp v152, v136 row_ror:1 row_mask:0xf bank_mask:0xf
	v_mov_b32_dpp v153, v137 row_ror:1 row_mask:0xf bank_mask:0xf
	v_mov_b32_dpp v184, v134 row_ror:2 row_mask:0xf bank_mask:0xf
	v_mov_b32_dpp v185, v135 row_ror:2 row_mask:0xf bank_mask:0xf
	v_mov_b32_dpp v186, v136 row_ror:2 row_mask:0xf bank_mask:0xf
	v_mov_b32_dpp v182, v137 row_ror:2 row_mask:0xf bank_mask:0xf
	v_cmp_gt_i32_e32 vcc, s86, v158
	v_lshlrev_b32_e32 v148, 1, v158
	v_cndmask_b32_e64 v138, v150, v196, s[8:9]
	v_cndmask_b32_e64 v142, v201, v184, s[10:11]
	v_cndmask_b32_e64 v139, v151, v197, s[8:9]
	v_cndmask_b32_e64 v143, v202, v185, s[10:11]
	v_cndmask_b32_e64 v140, v152, v198, s[8:9]
	v_cndmask_b32_e64 v144, v203, v186, s[10:11]
	v_cndmask_b32_e64 v141, v153, v199, s[8:9]
	v_cndmask_b32_e64 v145, v200, v182, s[10:11]
	s_and_b64 s[50:51], s[62:63], vcc
	v_add_u32_e32 v149, 0xffff8000, v148
	v_add_u32_e32 v148, 0xffff8001, v148
	s_and_saveexec_b64 s[0:1], s[50:51]
	s_cbranch_execz .LBB0_2314
	v_mov_b64_e32 v[138:139], s[60:61]
	v_mad_i64_i32 v[140:141], s[22:23], v149, s87, v[138:139]
	v_mad_i64_i32 v[138:139], s[22:23], v148, s87, v[138:139]
	v_lshl_add_u64 v[140:141], v[140:141], 0, v[176:177]
	v_lshl_add_u64 v[138:139], v[138:139], 0, v[176:177]
	global_load_dwordx4 v[142:145], v[140:141], off
	s_nop 0
	global_load_dwordx4 v[138:141], v[138:139], off
	s_waitcnt vmcnt(0)
.LBB0_2314:
	s_or_b64 exec, exec, s[0:1]
	v_pk_mul_f32 v[142:143], v[118:119], v[142:143]
	v_pk_mul_f32 v[144:145], v[120:121], v[144:145]
	v_pk_fma_f32 v[138:139], v[110:111], v[138:139], v[142:143]
	v_pk_fma_f32 v[140:141], v[112:113], v[140:141], v[144:145]
	v_pk_fma_f32 v[138:139], v[134:135], v[114:115], v[138:139]
	v_pk_fma_f32 v[140:141], v[136:137], v[116:117], v[140:141]
	v_pk_add_f32 v[138:139], v[102:103], v[138:139]
	v_pk_add_f32 v[140:141], v[104:105], v[140:141]
	v_mul_f32_e32 v142, 0x3d372713, v138
	v_mul_f32_e32 v143, 0x3d372713, v139
	v_mul_f32_e32 v142, v138, v142
	v_mul_f32_e32 v143, v139, v143
	v_mul_f32_e32 v144, 0x3d372713, v140
	v_mul_f32_e32 v145, 0x3d372713, v141
	v_fma_f32 v142, v138, v142, v138
	v_fma_f32 v143, v139, v143, v139
	v_mul_f32_e32 v144, v140, v144
	v_mul_f32_e32 v145, v141, v145
	v_mul_f32_e32 v142, 0xbfcc422a, v142
	v_mul_f32_e32 v143, 0xbfcc422a, v143
	v_fma_f32 v144, v140, v144, v140
	v_fma_f32 v145, v141, v145, v141
	v_mul_f32_e32 v142, 0x3fb8aa3b, v142
	v_mul_f32_e32 v143, 0x3fb8aa3b, v143
	v_mul_f32_e32 v144, 0xbfcc422a, v144
	v_mul_f32_e32 v145, 0xbfcc422a, v145
	v_exp_f32_e32 v142, v142
	v_exp_f32_e32 v143, v143
	v_mul_f32_e32 v144, 0x3fb8aa3b, v144
	v_mul_f32_e32 v145, 0x3fb8aa3b, v145
	v_exp_f32_e32 v144, v144
	v_exp_f32_e32 v145, v145
	v_add_f32_e32 v142, 1.0, v142
	v_add_f32_e32 v143, 1.0, v143
	v_rcp_f32_e32 v142, v142
	v_rcp_f32_e32 v143, v143
	v_add_f32_e32 v144, 1.0, v144
	v_add_f32_e32 v145, 1.0, v145
	v_rcp_f32_e32 v144, v144
	v_rcp_f32_e32 v145, v145
	v_pk_mul_f32 v[138:139], v[138:139], v[142:143]
	s_nop 0
	v_pk_mul_f32 v[130:131], v[130:131], v[138:139]
	v_pk_mul_f32 v[138:139], v[140:141], v[144:145]
	v_cvt_pk_bf16_f32 v130, v130, v131
	v_pk_mul_f32 v[132:133], v[132:133], v[138:139]
	v_lshl_add_u32 v140, v158, 1, v193
	v_cvt_pk_bf16_f32 v131, v132, v133
	v_mov_b64_e32 v[132:133], s[26:27]
	v_mad_i64_i32 v[132:133], s[0:1], v158, s81, v[132:133]
	v_lshl_add_u64 v[138:139], v[174:175], 1, v[132:133]
	global_store_dwordx2 v[138:139], v[130:131], off
	s_and_saveexec_b64 s[0:1], s[50:51]
	s_cbranch_execz .LBB0_2316
	v_mov_b64_e32 v[130:131], s[38:39]
	v_mad_i64_i32 v[130:131], s[22:23], v140, s87, v[130:131]
	v_lshl_add_u64 v[130:131], v[174:175], 2, v[130:131]
	global_store_dwordx4 v[130:131], v[134:137], off
.LBB0_2316:
	s_or_b64 exec, exec, s[0:1]
	v_mov_b32_e32 v143, 0
	v_mov_b32_e32 v144, 0
	v_mov_b32_e32 v145, 0
	v_mov_b32_dpp v143, v126 row_ror:1 row_mask:0xf bank_mask:0xf
	v_mov_b32_e32 v158, 0
	v_mov_b32_e32 v187, 0
	v_mov_b32_e32 v188, 0
	v_mov_b32_e32 v189, 0
	v_mov_b32_e32 v183, 0
	v_cndmask_b32_e64 v130, v143, v150, s[8:9]
	v_or_b32_e32 v150, 32, v194
	v_mov_b32_dpp v144, v127 row_ror:1 row_mask:0xf bank_mask:0xf
	v_mov_b32_dpp v145, v128 row_ror:1 row_mask:0xf bank_mask:0xf
	v_mov_b32_dpp v158, v129 row_ror:1 row_mask:0xf bank_mask:0xf
	v_mov_b32_dpp v187, v126 row_ror:2 row_mask:0xf bank_mask:0xf
	v_mov_b32_dpp v188, v127 row_ror:2 row_mask:0xf bank_mask:0xf
	v_mov_b32_dpp v189, v128 row_ror:2 row_mask:0xf bank_mask:0xf
	v_mov_b32_dpp v183, v129 row_ror:2 row_mask:0xf bank_mask:0xf
	v_cmp_gt_i32_e32 vcc, s86, v150
	v_lshlrev_b32_e32 v141, 1, v150
	v_cndmask_b32_e64 v134, v184, v187, s[10:11]
	v_cndmask_b32_e64 v131, v144, v151, s[8:9]
	v_cndmask_b32_e64 v135, v185, v188, s[10:11]
	v_cndmask_b32_e64 v132, v145, v152, s[8:9]
	v_cndmask_b32_e64 v136, v186, v189, s[10:11]
	v_cndmask_b32_e64 v133, v158, v153, s[8:9]
	v_cndmask_b32_e64 v137, v182, v183, s[10:11]
	s_and_b64 s[52:53], s[62:63], vcc
	v_add_u32_e32 v142, 0xffff8000, v141
	v_add_u32_e32 v141, 0xffff8001, v141
	s_and_saveexec_b64 s[0:1], s[52:53]
	s_cbranch_execz .LBB0_2318
	v_mov_b64_e32 v[130:131], s[60:61]
	v_mad_i64_i32 v[132:133], s[22:23], v142, s87, v[130:131]
	v_mad_i64_i32 v[130:131], s[22:23], v141, s87, v[130:131]
	v_lshl_add_u64 v[132:133], v[132:133], 0, v[176:177]
	v_lshl_add_u64 v[130:131], v[130:131], 0, v[176:177]
	global_load_dwordx4 v[134:137], v[132:133], off
	s_nop 0
	global_load_dwordx4 v[130:133], v[130:131], off
	s_waitcnt vmcnt(0)
.LBB0_2318:
	s_or_b64 exec, exec, s[0:1]
	v_pk_mul_f32 v[134:135], v[118:119], v[134:135]
	v_pk_mul_f32 v[136:137], v[120:121], v[136:137]
	v_pk_fma_f32 v[130:131], v[110:111], v[130:131], v[134:135]
	v_pk_fma_f32 v[132:133], v[112:113], v[132:133], v[136:137]
	v_pk_fma_f32 v[130:131], v[126:127], v[114:115], v[130:131]
	v_pk_fma_f32 v[132:133], v[128:129], v[116:117], v[132:133]
	v_pk_add_f32 v[130:131], v[102:103], v[130:131]
	v_pk_add_f32 v[132:133], v[104:105], v[132:133]
	v_mul_f32_e32 v134, 0x3d372713, v130
	v_mul_f32_e32 v135, 0x3d372713, v131
	v_mul_f32_e32 v134, v130, v134
	v_mul_f32_e32 v135, v131, v135
	v_mul_f32_e32 v136, 0x3d372713, v132
	v_mul_f32_e32 v137, 0x3d372713, v133
	v_fma_f32 v134, v130, v134, v130
	v_fma_f32 v135, v131, v135, v131
	v_mul_f32_e32 v136, v132, v136
	v_mul_f32_e32 v137, v133, v137
	v_mul_f32_e32 v134, 0xbfcc422a, v134
	v_mul_f32_e32 v135, 0xbfcc422a, v135
	v_fma_f32 v136, v132, v136, v132
	v_fma_f32 v137, v133, v137, v133
	v_mul_f32_e32 v134, 0x3fb8aa3b, v134
	v_mul_f32_e32 v135, 0x3fb8aa3b, v135
	v_mul_f32_e32 v136, 0xbfcc422a, v136
	v_mul_f32_e32 v137, 0xbfcc422a, v137
	v_exp_f32_e32 v134, v134
	v_exp_f32_e32 v135, v135
	v_mul_f32_e32 v136, 0x3fb8aa3b, v136
	v_mul_f32_e32 v137, 0x3fb8aa3b, v137
	v_exp_f32_e32 v136, v136
	v_exp_f32_e32 v137, v137
	v_add_f32_e32 v134, 1.0, v134
	v_add_f32_e32 v135, 1.0, v135
	v_rcp_f32_e32 v134, v134
	v_rcp_f32_e32 v135, v135
	v_add_f32_e32 v136, 1.0, v136
	v_add_f32_e32 v137, 1.0, v137
	v_rcp_f32_e32 v136, v136
	v_rcp_f32_e32 v137, v137
	v_pk_mul_f32 v[130:131], v[130:131], v[134:135]
	s_nop 0
	v_pk_mul_f32 v[122:123], v[122:123], v[130:131]
	v_pk_mul_f32 v[130:131], v[132:133], v[136:137]
	v_cvt_pk_bf16_f32 v122, v122, v123
	v_pk_mul_f32 v[124:125], v[124:125], v[130:131]
	v_lshl_add_u32 v137, v150, 1, v193
	v_cvt_pk_bf16_f32 v123, v124, v125
	v_mov_b64_e32 v[124:125], s[26:27]
	v_mad_i64_i32 v[124:125], s[0:1], v150, s81, v[124:125]
	v_lshl_add_u64 v[130:131], v[174:175], 1, v[124:125]
	global_store_dwordx2 v[130:131], v[122:123], off
	s_and_saveexec_b64 s[0:1], s[52:53]
	s_cbranch_execz .LBB0_2320
	v_mov_b64_e32 v[122:123], s[38:39]
	v_mad_i64_i32 v[122:123], s[22:23], v137, s87, v[122:123]
	v_lshl_add_u64 v[122:123], v[174:175], 2, v[122:123]
	global_store_dwordx4 v[122:123], v[126:129], off
.LBB0_2320:
	s_or_b64 exec, exec, s[0:1]
	v_mov_b32_e32 v122, 0
	v_mov_b32_e32 v123, 0
	v_mov_b32_e32 v124, 0
	v_mov_b32_e32 v125, 0
	v_mov_b32_e32 v126, 0
	v_mov_b32_e32 v127, 0
	v_mov_b32_e32 v128, 0
	v_mov_b32_e32 v129, 0
	v_or_b32_e32 v135, 48, v194
	v_mov_b32_dpp v122, v98 row_ror:1 row_mask:0xf bank_mask:0xf
	v_mov_b32_dpp v123, v99 row_ror:1 row_mask:0xf bank_mask:0xf
	v_mov_b32_dpp v124, v100 row_ror:1 row_mask:0xf bank_mask:0xf
	v_mov_b32_dpp v125, v101 row_ror:1 row_mask:0xf bank_mask:0xf
	v_mov_b32_dpp v126, v98 row_ror:2 row_mask:0xf bank_mask:0xf
	v_mov_b32_dpp v127, v99 row_ror:2 row_mask:0xf bank_mask:0xf
	v_mov_b32_dpp v128, v100 row_ror:2 row_mask:0xf bank_mask:0xf
	v_mov_b32_dpp v129, v101 row_ror:2 row_mask:0xf bank_mask:0xf
	v_cmp_gt_i32_e64 s[22:23], s86, v135
	v_lshlrev_b32_e32 v132, 1, v135
	v_cndmask_b32_e64 v122, v122, v143, s[8:9]
	v_cndmask_b32_e64 v126, v187, v126, s[10:11]
	v_cndmask_b32_e64 v123, v123, v144, s[8:9]
	v_cndmask_b32_e64 v127, v188, v127, s[10:11]
	v_cndmask_b32_e64 v124, v124, v145, s[8:9]
	v_cndmask_b32_e64 v128, v189, v128, s[10:11]
	v_cndmask_b32_e64 v125, v125, v158, s[8:9]
	v_cndmask_b32_e64 v129, v183, v129, s[10:11]
	s_and_b64 s[58:59], s[62:63], s[22:23]
	v_add_u32_e32 v144, 0xffff8000, v132
	v_add_u32_e32 v143, 0xffff8001, v132
	s_and_saveexec_b64 s[0:1], s[58:59]
	s_cbranch_execz .LBB0_2322
	v_mov_b64_e32 v[122:123], s[60:61]
	v_mad_i64_i32 v[124:125], s[24:25], v144, s87, v[122:123]
	v_mad_i64_i32 v[122:123], s[24:25], v143, s87, v[122:123]
	v_lshl_add_u64 v[124:125], v[124:125], 0, v[176:177]
	v_lshl_add_u64 v[122:123], v[122:123], 0, v[176:177]
	global_load_dwordx4 v[126:129], v[124:125], off
	s_nop 0
	global_load_dwordx4 v[122:125], v[122:123], off
	s_waitcnt vmcnt(0)
.LBB0_2322:
	s_or_b64 exec, exec, s[0:1]
	v_pk_mul_f32 v[126:127], v[118:119], v[126:127]
	v_pk_mul_f32 v[128:129], v[120:121], v[128:129]
	v_pk_fma_f32 v[122:123], v[110:111], v[122:123], v[126:127]
	v_pk_fma_f32 v[124:125], v[112:113], v[124:125], v[128:129]
	v_pk_fma_f32 v[122:123], v[98:99], v[114:115], v[122:123]
	v_pk_fma_f32 v[124:125], v[100:101], v[116:117], v[124:125]
	v_pk_add_f32 v[122:123], v[102:103], v[122:123]
	v_pk_add_f32 v[124:125], v[104:105], v[124:125]
	v_mul_f32_e32 v126, 0x3d372713, v122
	v_mul_f32_e32 v127, 0x3d372713, v123
	v_mul_f32_e32 v126, v122, v126
	v_mul_f32_e32 v127, v123, v127
	v_fma_f32 v126, v122, v126, v122
	v_fma_f32 v127, v123, v127, v123
	v_mul_f32_e32 v128, 0x3d372713, v124
	v_mul_f32_e32 v129, 0x3d372713, v125
	v_mul_f32_e32 v126, 0xbfcc422a, v126
	v_mul_f32_e32 v127, 0xbfcc422a, v127
	v_mul_f32_e32 v128, v124, v128
	v_mul_f32_e32 v129, v125, v129
	v_mul_f32_e32 v126, 0x3fb8aa3b, v126
	v_mul_f32_e32 v127, 0x3fb8aa3b, v127
	v_fma_f32 v128, v124, v128, v124
	v_fma_f32 v129, v125, v129, v125
	v_exp_f32_e32 v126, v126
	v_exp_f32_e32 v127, v127
	v_mul_f32_e32 v128, 0xbfcc422a, v128
	v_mul_f32_e32 v129, 0xbfcc422a, v129
	v_mul_f32_e32 v128, 0x3fb8aa3b, v128
	v_mul_f32_e32 v129, 0x3fb8aa3b, v129
	v_exp_f32_e32 v128, v128
	v_exp_f32_e32 v129, v129
	v_add_f32_e32 v126, 1.0, v126
	v_add_f32_e32 v127, 1.0, v127
	v_rcp_f32_e32 v126, v126
	v_rcp_f32_e32 v127, v127
	v_add_f32_e32 v128, 1.0, v128
	v_add_f32_e32 v129, 1.0, v129
	v_rcp_f32_e32 v128, v128
	v_rcp_f32_e32 v129, v129
	v_pk_mul_f32 v[122:123], v[122:123], v[126:127]
	s_ashr_i32 s0, s64, 12
	v_pk_mul_f32 v[122:123], v[106:107], v[122:123]
	v_pk_mul_f32 v[124:125], v[124:125], v[128:129]
	v_cvt_pk_bf16_f32 v126, v122, v123
	v_mov_b64_e32 v[122:123], s[26:27]
	s_and_b32 s91, s0, -2
	v_pk_mul_f32 v[124:125], v[108:109], v[124:125]
	v_mad_i64_i32 v[122:123], s[0:1], v135, s81, v[122:123]
	v_and_b32_e32 v145, 0x1fff, v135
	s_addk_i32 s91, 0xe002
	v_cvt_pk_bf16_f32 v127, v124, v125
	v_lshl_add_u64 v[122:123], v[174:175], 1, v[122:123]
	s_mov_b64 s[24:25], -1
	s_and_b64 vcc, exec, s[20:21]
	v_cmp_lt_u32_e64 s[0:1], s88, v145
	global_store_dwordx2 v[122:123], v[126:127], off
	s_cbranch_vccnz .LBB0_2331
	s_and_saveexec_b64 s[24:25], s[0:1]
	s_cbranch_execz .LBB0_2325
	v_add_u32_e32 v124, s91, v145
	v_mul_hi_i32_i24_e32 v125, 0x2c00, v124
	v_mul_i32_i24_e32 v124, 0x2c00, v124
	v_lshl_add_u64 v[124:125], s[40:41], 0, v[124:125]
	v_lshl_add_u64 v[124:125], v[174:175], 2, v[124:125]
	global_store_dwordx4 v[124:125], v[98:101], off

.LBB0_2353:
	v_mov_b32_e32 v100, 0
	v_mov_b32_e32 v101, 0
	v_mov_b32_e32 v106, 0
	v_mov_b32_e32 v124, 0
	v_mov_b32_e32 v126, 0
	v_mov_b32_e32 v128, 0
	v_mov_b32_e32 v129, 0
	v_mov_b32_e32 v125, 0
	v_or_b32_e32 v109, 16, v134
	v_mov_b32_dpp v100, v86 row_ror:1 row_mask:0xf bank_mask:0xf
	v_mov_b32_dpp v101, v87 row_ror:1 row_mask:0xf bank_mask:0xf
	v_mov_b32_dpp v106, v88 row_ror:1 row_mask:0xf bank_mask:0xf
	v_mov_b32_dpp v124, v89 row_ror:1 row_mask:0xf bank_mask:0xf
	v_mov_b32_dpp v126, v86 row_ror:2 row_mask:0xf bank_mask:0xf
	v_mov_b32_dpp v128, v87 row_ror:2 row_mask:0xf bank_mask:0xf
	v_mov_b32_dpp v129, v88 row_ror:2 row_mask:0xf bank_mask:0xf
	v_mov_b32_dpp v125, v89 row_ror:2 row_mask:0xf bank_mask:0xf
	v_cmp_gt_i32_e32 vcc, s86, v109
	v_lshlrev_b32_e32 v107, 1, v109
	v_cndmask_b32_e64 v90, v100, v150, s[8:9]
	v_cndmask_b32_e64 v94, v183, v126, s[10:11]
	v_cndmask_b32_e64 v91, v101, v151, s[8:9]
	v_cndmask_b32_e64 v95, v184, v128, s[10:11]
	v_cndmask_b32_e64 v92, v106, v152, s[8:9]
	v_cndmask_b32_e64 v96, v185, v129, s[10:11]
	v_cndmask_b32_e64 v93, v124, v153, s[8:9]
	v_cndmask_b32_e64 v97, v182, v125, s[10:11]
	s_and_b64 s[54:55], s[62:63], vcc
	v_add_u32_e32 v108, 0xffff8000, v107
	v_add_u32_e32 v107, 0xffff8001, v107
	s_and_saveexec_b64 s[0:1], s[54:55]
	s_cbranch_execz .LBB0_2355
	v_mov_b64_e32 v[90:91], s[60:61]
	v_mad_i64_i32 v[92:93], s[24:25], v108, s87, v[90:91]
	v_mad_i64_i32 v[90:91], s[24:25], v107, s87, v[90:91]
	v_lshl_add_u64 v[92:93], v[92:93], 0, v[176:177]
	v_lshl_add_u64 v[90:91], v[90:91], 0, v[176:177]
	global_load_dwordx4 v[94:97], v[92:93], off
	s_nop 0
	global_load_dwordx4 v[90:93], v[90:91], off
	s_waitcnt vmcnt(0)
.LBB0_2355:
	s_or_b64 exec, exec, s[0:1]
	v_pk_mul_f32 v[94:95], v[118:119], v[94:95]
	v_pk_mul_f32 v[96:97], v[120:121], v[96:97]
	v_pk_fma_f32 v[90:91], v[110:111], v[90:91], v[94:95]
	v_pk_fma_f32 v[92:93], v[112:113], v[92:93], v[96:97]
	v_pk_fma_f32 v[90:91], v[86:87], v[114:115], v[90:91]
	v_pk_fma_f32 v[92:93], v[88:89], v[116:117], v[92:93]
	v_pk_add_f32 v[90:91], v[102:103], v[90:91]
	v_pk_add_f32 v[92:93], v[104:105], v[92:93]
	v_mul_f32_e32 v94, 0x3d372713, v90
	v_mul_f32_e32 v95, 0x3d372713, v91
	v_mul_f32_e32 v94, v90, v94
	v_mul_f32_e32 v95, v91, v95
	v_mul_f32_e32 v96, 0x3d372713, v92
	v_mul_f32_e32 v97, 0x3d372713, v93
	v_fma_f32 v94, v90, v94, v90
	v_fma_f32 v95, v91, v95, v91
	v_mul_f32_e32 v96, v92, v96
	v_mul_f32_e32 v97, v93, v97
	v_mul_f32_e32 v94, 0xbfcc422a, v94
	v_mul_f32_e32 v95, 0xbfcc422a, v95
	v_fma_f32 v96, v92, v96, v92
	v_fma_f32 v97, v93, v97, v93
	v_mul_f32_e32 v94, 0x3fb8aa3b, v94
	v_mul_f32_e32 v95, 0x3fb8aa3b, v95
	v_mul_f32_e32 v96, 0xbfcc422a, v96
	v_mul_f32_e32 v97, 0xbfcc422a, v97
	v_exp_f32_e32 v94, v94
	v_exp_f32_e32 v95, v95
	v_mul_f32_e32 v96, 0x3fb8aa3b, v96
	v_mul_f32_e32 v97, 0x3fb8aa3b, v97
	v_exp_f32_e32 v96, v96
	v_exp_f32_e32 v97, v97
	v_add_f32_e32 v94, 1.0, v94
	v_add_f32_e32 v95, 1.0, v95
	v_rcp_f32_e32 v94, v94
	v_rcp_f32_e32 v95, v95
	v_add_f32_e32 v96, 1.0, v96
	v_add_f32_e32 v97, 1.0, v97
	v_rcp_f32_e32 v96, v96
	v_rcp_f32_e32 v97, v97
	v_pk_mul_f32 v[90:91], v[90:91], v[94:95]
	s_nop 0
	v_pk_mul_f32 v[82:83], v[82:83], v[90:91]
	v_pk_mul_f32 v[90:91], v[92:93], v[96:97]
	v_cvt_pk_bf16_f32 v82, v82, v83
	v_pk_mul_f32 v[84:85], v[84:85], v[90:91]
	s_nop 0
	v_cvt_pk_bf16_f32 v83, v84, v85
	v_mov_b64_e32 v[84:85], s[26:27]
	v_mad_i64_i32 v[84:85], s[0:1], v109, s81, v[84:85]
	v_lshl_add_u64 v[90:91], v[174:175], 1, v[84:85]
	v_lshl_add_u32 v109, v109, 1, v193
	global_store_dwordx2 v[90:91], v[82:83], off
	s_and_saveexec_b64 s[0:1], s[54:55]
	s_cbranch_execz .LBB0_2357
	v_mov_b64_e32 v[82:83], s[38:39]
	v_mad_i64_i32 v[82:83], s[24:25], v109, s87, v[82:83]
	v_lshl_add_u64 v[82:83], v[174:175], 2, v[82:83]
	global_store_dwordx4 v[82:83], v[86:89], off
.LBB0_2357:
	s_or_b64 exec, exec, s[0:1]
	v_mov_b32_e32 v94, 0
	v_mov_b32_e32 v95, 0
	v_mov_b32_e32 v96, 0
	v_mov_b32_dpp v94, v78 row_ror:1 row_mask:0xf bank_mask:0xf
	v_mov_b32_e32 v97, 0
	v_mov_b32_e32 v132, 0
	v_mov_b32_e32 v133, 0
	v_mov_b32_e32 v150, 0
	v_mov_b32_e32 v127, 0
	v_cndmask_b32_e64 v82, v94, v100, s[8:9]
	v_or_b32_e32 v100, 32, v134
	v_mov_b32_dpp v95, v79 row_ror:1 row_mask:0xf bank_mask:0xf
	v_mov_b32_dpp v96, v80 row_ror:1 row_mask:0xf bank_mask:0xf
	v_mov_b32_dpp v97, v81 row_ror:1 row_mask:0xf bank_mask:0xf
	v_mov_b32_dpp v132, v78 row_ror:2 row_mask:0xf bank_mask:0xf
	v_mov_b32_dpp v133, v79 row_ror:2 row_mask:0xf bank_mask:0xf
	v_mov_b32_dpp v150, v80 row_ror:2 row_mask:0xf bank_mask:0xf
	v_mov_b32_dpp v127, v81 row_ror:2 row_mask:0xf bank_mask:0xf
	v_cmp_gt_i32_e32 vcc, s86, v100
	v_lshlrev_b32_e32 v92, 1, v100
	v_cndmask_b32_e64 v86, v126, v132, s[10:11]
	v_cndmask_b32_e64 v83, v95, v101, s[8:9]
	v_cndmask_b32_e64 v87, v128, v133, s[10:11]
	v_cndmask_b32_e64 v84, v96, v106, s[8:9]
	v_cndmask_b32_e64 v88, v129, v150, s[10:11]
	v_cndmask_b32_e64 v85, v97, v124, s[8:9]
	v_cndmask_b32_e64 v89, v125, v127, s[10:11]
	s_and_b64 s[56:57], s[62:63], vcc
	v_add_u32_e32 v125, 0xffff8000, v92
	v_add_u32_e32 v124, 0xffff8001, v92
	s_and_saveexec_b64 s[0:1], s[56:57]
	s_cbranch_execz .LBB0_2359
	v_mov_b64_e32 v[82:83], s[60:61]
	v_mad_i64_i32 v[84:85], s[24:25], v125, s87, v[82:83]
	v_mad_i64_i32 v[82:83], s[24:25], v124, s87, v[82:83]
	v_lshl_add_u64 v[84:85], v[84:85], 0, v[176:177]
	v_lshl_add_u64 v[82:83], v[82:83], 0, v[176:177]
	global_load_dwordx4 v[86:89], v[84:85], off
	s_nop 0
	global_load_dwordx4 v[82:85], v[82:83], off
	s_waitcnt vmcnt(0)
.LBB0_2359:
	s_or_b64 exec, exec, s[0:1]
	v_pk_mul_f32 v[86:87], v[118:119], v[86:87]
	v_pk_mul_f32 v[88:89], v[120:121], v[88:89]
	v_pk_fma_f32 v[82:83], v[110:111], v[82:83], v[86:87]
	v_pk_fma_f32 v[84:85], v[112:113], v[84:85], v[88:89]
	v_pk_fma_f32 v[82:83], v[78:79], v[114:115], v[82:83]
	v_pk_fma_f32 v[84:85], v[80:81], v[116:117], v[84:85]
	v_pk_add_f32 v[82:83], v[102:103], v[82:83]
	v_pk_add_f32 v[84:85], v[104:105], v[84:85]
	v_mul_f32_e32 v86, 0x3d372713, v82
	v_mul_f32_e32 v87, 0x3d372713, v83
	v_mul_f32_e32 v86, v82, v86
	v_mul_f32_e32 v87, v83, v87
	v_mul_f32_e32 v88, 0x3d372713, v84
	v_mul_f32_e32 v89, 0x3d372713, v85
	v_fma_f32 v86, v82, v86, v82
	v_fma_f32 v87, v83, v87, v83
	v_mul_f32_e32 v88, v84, v88
	v_mul_f32_e32 v89, v85, v89
	v_mul_f32_e32 v86, 0xbfcc422a, v86
	v_mul_f32_e32 v87, 0xbfcc422a, v87
	v_fma_f32 v88, v84, v88, v84
	v_fma_f32 v89, v85, v89, v85
	v_mul_f32_e32 v86, 0x3fb8aa3b, v86
	v_mul_f32_e32 v87, 0x3fb8aa3b, v87
	v_mul_f32_e32 v88, 0xbfcc422a, v88
	v_mul_f32_e32 v89, 0xbfcc422a, v89
	v_exp_f32_e32 v86, v86
	v_exp_f32_e32 v87, v87
	v_mul_f32_e32 v88, 0x3fb8aa3b, v88
	v_mul_f32_e32 v89, 0x3fb8aa3b, v89
	v_exp_f32_e32 v88, v88
	v_exp_f32_e32 v89, v89
	v_add_f32_e32 v86, 1.0, v86
	v_add_f32_e32 v87, 1.0, v87
	v_rcp_f32_e32 v86, v86
	v_rcp_f32_e32 v87, v87
	v_add_f32_e32 v88, 1.0, v88
	v_add_f32_e32 v89, 1.0, v89
	v_rcp_f32_e32 v88, v88
	v_rcp_f32_e32 v89, v89
	v_pk_mul_f32 v[82:83], v[82:83], v[86:87]
	v_lshl_add_u32 v126, v100, 1, v193
	v_pk_mul_f32 v[74:75], v[74:75], v[82:83]
	v_pk_mul_f32 v[82:83], v[84:85], v[88:89]
	v_cvt_pk_bf16_f32 v74, v74, v75
	v_pk_mul_f32 v[76:77], v[76:77], v[82:83]
	s_nop 0
	v_cvt_pk_bf16_f32 v75, v76, v77
	v_mov_b64_e32 v[76:77], s[26:27]
	v_mad_i64_i32 v[76:77], s[0:1], v100, s81, v[76:77]
	v_lshl_add_u64 v[92:93], v[174:175], 1, v[76:77]
	global_store_dwordx2 v[92:93], v[74:75], off
	s_and_saveexec_b64 s[0:1], s[56:57]
	s_cbranch_execz .LBB0_2361
	v_mov_b64_e32 v[74:75], s[38:39]
	v_mad_i64_i32 v[74:75], s[24:25], v126, s87, v[74:75]
	v_lshl_add_u64 v[74:75], v[174:175], 2, v[74:75]
	global_store_dwordx4 v[74:75], v[78:81], off
.LBB0_2361:
	s_or_b64 exec, exec, s[0:1]
	v_mov_b32_e32 v74, 0
	v_mov_b32_e32 v75, 0
	v_mov_b32_e32 v76, 0
	v_mov_b32_e32 v77, 0
	v_mov_b32_e32 v78, 0
	v_mov_b32_e32 v79, 0
	v_mov_b32_e32 v80, 0
	v_mov_b32_e32 v81, 0
	v_or_b32_e32 v106, 48, v134
	v_mov_b32_dpp v74, v66 row_ror:1 row_mask:0xf bank_mask:0xf
	v_mov_b32_dpp v75, v67 row_ror:1 row_mask:0xf bank_mask:0xf
	v_mov_b32_dpp v76, v68 row_ror:1 row_mask:0xf bank_mask:0xf
	v_mov_b32_dpp v77, v69 row_ror:1 row_mask:0xf bank_mask:0xf
	v_mov_b32_dpp v78, v66 row_ror:2 row_mask:0xf bank_mask:0xf
	v_mov_b32_dpp v79, v67 row_ror:2 row_mask:0xf bank_mask:0xf
	v_mov_b32_dpp v80, v68 row_ror:2 row_mask:0xf bank_mask:0xf
	v_mov_b32_dpp v81, v69 row_ror:2 row_mask:0xf bank_mask:0xf
	v_cmp_gt_i32_e64 s[24:25], s86, v106
	v_lshlrev_b32_e32 v82, 1, v106
	v_cndmask_b32_e64 v74, v74, v94, s[8:9]
	v_cndmask_b32_e64 v78, v132, v78, s[10:11]
	v_cndmask_b32_e64 v75, v75, v95, s[8:9]
	v_cndmask_b32_e64 v79, v133, v79, s[10:11]
	v_cndmask_b32_e64 v76, v76, v96, s[8:9]
	v_cndmask_b32_e64 v80, v150, v80, s[10:11]
	v_cndmask_b32_e64 v77, v77, v97, s[8:9]
	v_cndmask_b32_e64 v81, v127, v81, s[10:11]
	s_and_b64 s[62:63], s[62:63], s[24:25]
	v_add_u32_e32 v128, 0xffff8000, v82
	v_add_u32_e32 v127, 0xffff8001, v82
	s_and_saveexec_b64 s[0:1], s[62:63]
	s_cbranch_execz .LBB0_2363
	v_mov_b64_e32 v[74:75], s[60:61]
	v_mad_i64_i32 v[76:77], s[92:93], v128, s87, v[74:75]
	v_mad_i64_i32 v[74:75], s[92:93], v127, s87, v[74:75]
	v_lshl_add_u64 v[76:77], v[76:77], 0, v[176:177]
	v_lshl_add_u64 v[74:75], v[74:75], 0, v[176:177]
	global_load_dwordx4 v[78:81], v[76:77], off
	s_nop 0
	global_load_dwordx4 v[74:77], v[74:75], off
	s_waitcnt vmcnt(0)
.LBB0_2363:
	s_or_b64 exec, exec, s[0:1]
	v_pk_mul_f32 v[80:81], v[120:121], v[80:81]
	v_pk_mul_f32 v[78:79], v[118:119], v[78:79]
	v_pk_fma_f32 v[76:77], v[112:113], v[76:77], v[80:81]
	v_pk_fma_f32 v[74:75], v[110:111], v[74:75], v[78:79]
	v_pk_fma_f32 v[76:77], v[68:69], v[116:117], v[76:77]
	v_pk_fma_f32 v[74:75], v[66:67], v[114:115], v[74:75]
	v_pk_add_f32 v[76:77], v[104:105], v[76:77]
	v_pk_add_f32 v[74:75], v[102:103], v[74:75]
	v_mul_f32_e32 v80, 0x3d372713, v76
	v_mul_f32_e32 v78, 0x3d372713, v74
	v_mul_f32_e32 v79, 0x3d372713, v75
	v_mul_f32_e32 v81, 0x3d372713, v77
	v_mul_f32_e32 v78, v74, v78
	v_mul_f32_e32 v79, v75, v79
	v_mul_f32_e32 v80, v76, v80
	v_mul_f32_e32 v81, v77, v81
	v_fma_f32 v78, v74, v78, v74
	v_fma_f32 v79, v75, v79, v75
	v_fma_f32 v80, v76, v80, v76
	v_fma_f32 v81, v77, v81, v77
	v_mul_f32_e32 v78, 0xbfcc422a, v78
	v_mul_f32_e32 v79, 0xbfcc422a, v79
	v_mul_f32_e32 v80, 0xbfcc422a, v80
	v_mul_f32_e32 v81, 0xbfcc422a, v81
	v_mul_f32_e32 v78, 0x3fb8aa3b, v78
	v_mul_f32_e32 v79, 0x3fb8aa3b, v79
	v_mul_f32_e32 v80, 0x3fb8aa3b, v80
	v_mul_f32_e32 v81, 0x3fb8aa3b, v81
	v_exp_f32_e32 v78, v78
	v_exp_f32_e32 v79, v79
	v_exp_f32_e32 v80, v80
	v_exp_f32_e32 v81, v81
	v_add_f32_e32 v78, 1.0, v78
	v_add_f32_e32 v79, 1.0, v79
	v_add_f32_e32 v80, 1.0, v80
	v_add_f32_e32 v81, 1.0, v81
	v_rcp_f32_e32 v78, v78
	v_rcp_f32_e32 v79, v79
	v_rcp_f32_e32 v80, v80
	v_rcp_f32_e32 v81, v81
	s_ashr_i32 s0, s64, 12
	v_pk_mul_f32 v[74:75], v[74:75], v[78:79]
	s_and_b32 s92, s0, -2
	v_pk_mul_f32 v[76:77], v[76:77], v[80:81]
	v_pk_mul_f32 v[74:75], v[70:71], v[74:75]
	v_pk_mul_f32 v[76:77], v[72:73], v[76:77]
	v_cvt_pk_bf16_f32 v74, v74, v75
	v_cvt_pk_bf16_f32 v75, v76, v77
	v_mov_b64_e32 v[76:77], s[26:27]
	v_mad_i64_i32 v[76:77], s[0:1], v106, s81, v[76:77]
	v_and_b32_e32 v110, 0x1fff, v106
	s_addk_i32 s92, 0xe002
	v_lshl_add_u64 v[94:95], v[174:175], 1, v[76:77]
	s_mov_b64 s[64:65], -1
	s_and_b64 vcc, exec, s[20:21]
	v_cmp_lt_u32_e64 s[0:1], s88, v110
	global_store_dwordx2 v[94:95], v[74:75], off
	s_cbranch_vccnz .LBB0_2372
	s_and_saveexec_b64 s[64:65], s[0:1]
	s_cbranch_execz .LBB0_2366
	v_add_u32_e32 v74, s92, v110
	v_mul_hi_i32_i24_e32 v75, 0x2c00, v74
	v_mul_i32_i24_e32 v74, 0x2c00, v74
	v_lshl_add_u64 v[74:75], s[40:41], 0, v[74:75]
	v_lshl_add_u64 v[74:75], v[174:175], 2, v[74:75]
	global_store_dwordx4 v[74:75], v[66:69], off

.LBB0_2394:
	v_mov_b32_e32 v82, 0
	v_mov_b32_e32 v83, 0
	v_mov_b32_e32 v84, 0
	v_mov_b32_e32 v85, 0
	v_mov_b32_e32 v87, 0
	v_mov_b32_e32 v88, 0
	v_mov_b32_e32 v89, 0
	v_mov_b32_e32 v86, 0
	v_mov_b32_dpp v82, v54 row_ror:1 row_mask:0xf bank_mask:0xf
	v_mov_b32_dpp v83, v55 row_ror:1 row_mask:0xf bank_mask:0xf
	v_mov_b32_dpp v84, v56 row_ror:1 row_mask:0xf bank_mask:0xf
	v_mov_b32_dpp v85, v57 row_ror:1 row_mask:0xf bank_mask:0xf
	v_mov_b32_dpp v87, v54 row_ror:2 row_mask:0xf bank_mask:0xf
	v_mov_b32_dpp v88, v55 row_ror:2 row_mask:0xf bank_mask:0xf
	v_mov_b32_dpp v89, v56 row_ror:2 row_mask:0xf bank_mask:0xf
	v_mov_b32_dpp v86, v57 row_ror:2 row_mask:0xf bank_mask:0xf
	v_cndmask_b32_e64 v58, v82, v111, s[8:9]
	v_cndmask_b32_e64 v62, v116, v87, s[10:11]
	v_cndmask_b32_e64 v59, v83, v112, s[8:9]
	v_cndmask_b32_e64 v63, v117, v88, s[10:11]
	v_cndmask_b32_e64 v60, v84, v113, s[8:9]
	v_cndmask_b32_e64 v64, v118, v89, s[10:11]
	v_cndmask_b32_e64 v61, v85, v114, s[8:9]
	v_cndmask_b32_e64 v65, v115, v86, s[10:11]
	s_and_saveexec_b64 s[0:1], s[50:51]
	s_cbranch_execz .LBB0_2396
	v_mov_b64_e32 v[58:59], s[60:61]
	v_mad_i64_i32 v[60:61], s[64:65], v149, s87, v[58:59]
	v_mad_i64_i32 v[58:59], s[64:65], v148, s87, v[58:59]
	v_lshl_add_u64 v[60:61], v[60:61], 0, v[176:177]
	v_lshl_add_u64 v[58:59], v[58:59], 0, v[176:177]
	global_load_dwordx4 v[62:65], v[60:61], off offset:64
	s_nop 0
	global_load_dwordx4 v[58:61], v[58:59], off offset:64
	s_waitcnt vmcnt(0)
.LBB0_2396:
	s_or_b64 exec, exec, s[0:1]
	v_pk_mul_f32 v[62:63], v[78:79], v[62:63]
	v_pk_mul_f32 v[64:65], v[80:81], v[64:65]
	v_pk_fma_f32 v[58:59], v[74:75], v[58:59], v[62:63]
	v_pk_fma_f32 v[60:61], v[76:77], v[60:61], v[64:65]
	v_pk_fma_f32 v[58:59], v[54:55], v[70:71], v[58:59]
	v_pk_fma_f32 v[60:61], v[56:57], v[72:73], v[60:61]
	v_pk_add_f32 v[58:59], v[66:67], v[58:59]
	v_pk_add_f32 v[60:61], v[68:69], v[60:61]
	v_mul_f32_e32 v62, 0x3d372713, v58
	v_mul_f32_e32 v63, 0x3d372713, v59
	v_mul_f32_e32 v62, v58, v62
	v_mul_f32_e32 v63, v59, v63
	v_mul_f32_e32 v64, 0x3d372713, v60
	v_mul_f32_e32 v65, 0x3d372713, v61
	v_fma_f32 v62, v58, v62, v58
	v_fma_f32 v63, v59, v63, v59
	v_mul_f32_e32 v64, v60, v64
	v_mul_f32_e32 v65, v61, v65
	v_mul_f32_e32 v62, 0xbfcc422a, v62
	v_mul_f32_e32 v63, 0xbfcc422a, v63
	v_fma_f32 v64, v60, v64, v60
	v_fma_f32 v65, v61, v65, v61
	v_mul_f32_e32 v62, 0x3fb8aa3b, v62
	v_mul_f32_e32 v63, 0x3fb8aa3b, v63
	v_mul_f32_e32 v64, 0xbfcc422a, v64
	v_mul_f32_e32 v65, 0xbfcc422a, v65
	v_exp_f32_e32 v62, v62
	v_exp_f32_e32 v63, v63
	v_mul_f32_e32 v64, 0x3fb8aa3b, v64
	v_mul_f32_e32 v65, 0x3fb8aa3b, v65
	v_exp_f32_e32 v64, v64
	v_exp_f32_e32 v65, v65
	v_add_f32_e32 v62, 1.0, v62
	v_add_f32_e32 v63, 1.0, v63
	v_rcp_f32_e32 v62, v62
	v_rcp_f32_e32 v63, v63
	v_add_f32_e32 v64, 1.0, v64
	v_add_f32_e32 v65, 1.0, v65
	v_rcp_f32_e32 v64, v64
	v_rcp_f32_e32 v65, v65
	v_pk_mul_f32 v[58:59], v[58:59], v[62:63]
	s_nop 0
	v_pk_mul_f32 v[50:51], v[50:51], v[58:59]
	v_pk_mul_f32 v[58:59], v[60:61], v[64:65]
	v_cvt_pk_bf16_f32 v50, v50, v51
	v_pk_mul_f32 v[52:53], v[52:53], v[58:59]
	s_nop 0
	v_cvt_pk_bf16_f32 v51, v52, v53
	global_store_dwordx2 v[138:139], v[50:51], off offset:32
	s_and_saveexec_b64 s[0:1], s[50:51]
	s_cbranch_execz .LBB0_2398
	v_mov_b64_e32 v[50:51], s[38:39]
	v_mad_i64_i32 v[50:51], s[50:51], v140, s87, v[50:51]
	v_lshl_add_u64 v[50:51], v[174:175], 2, v[50:51]
	global_store_dwordx4 v[50:51], v[54:57], off offset:64
.LBB0_2398:
	s_or_b64 exec, exec, s[0:1]
	v_mov_b32_e32 v58, 0
	v_mov_b32_e32 v59, 0
	v_mov_b32_e32 v60, 0
	v_mov_b32_e32 v61, 0
	v_mov_b32_e32 v63, 0
	v_mov_b32_e32 v64, 0
	v_mov_b32_e32 v65, 0
	v_mov_b32_e32 v62, 0
	v_mov_b32_dpp v58, v46 row_ror:1 row_mask:0xf bank_mask:0xf
	v_mov_b32_dpp v59, v47 row_ror:1 row_mask:0xf bank_mask:0xf
	v_mov_b32_dpp v60, v48 row_ror:1 row_mask:0xf bank_mask:0xf
	v_mov_b32_dpp v61, v49 row_ror:1 row_mask:0xf bank_mask:0xf
	v_mov_b32_dpp v63, v46 row_ror:2 row_mask:0xf bank_mask:0xf
	v_mov_b32_dpp v64, v47 row_ror:2 row_mask:0xf bank_mask:0xf
	v_mov_b32_dpp v65, v48 row_ror:2 row_mask:0xf bank_mask:0xf
	v_mov_b32_dpp v62, v49 row_ror:2 row_mask:0xf bank_mask:0xf
	v_cndmask_b32_e64 v50, v58, v82, s[8:9]
	v_cndmask_b32_e64 v54, v87, v63, s[10:11]
	v_cndmask_b32_e64 v51, v59, v83, s[8:9]
	v_cndmask_b32_e64 v55, v88, v64, s[10:11]
	v_cndmask_b32_e64 v52, v60, v84, s[8:9]
	v_cndmask_b32_e64 v56, v89, v65, s[10:11]
	v_cndmask_b32_e64 v53, v61, v85, s[8:9]
	v_cndmask_b32_e64 v57, v86, v62, s[10:11]
	s_and_saveexec_b64 s[0:1], s[52:53]
	s_cbranch_execz .LBB0_2400
	v_mov_b64_e32 v[50:51], s[60:61]
	v_mad_i64_i32 v[52:53], s[50:51], v142, s87, v[50:51]
	v_mad_i64_i32 v[50:51], s[50:51], v141, s87, v[50:51]
	v_lshl_add_u64 v[52:53], v[52:53], 0, v[176:177]
	v_lshl_add_u64 v[50:51], v[50:51], 0, v[176:177]
	global_load_dwordx4 v[54:57], v[52:53], off offset:64
	s_nop 0
	global_load_dwordx4 v[50:53], v[50:51], off offset:64
	s_waitcnt vmcnt(0)
.LBB0_2400:
	s_or_b64 exec, exec, s[0:1]
	v_pk_mul_f32 v[54:55], v[78:79], v[54:55]
	v_pk_mul_f32 v[56:57], v[80:81], v[56:57]
	v_pk_fma_f32 v[50:51], v[74:75], v[50:51], v[54:55]
	v_pk_fma_f32 v[52:53], v[76:77], v[52:53], v[56:57]
	v_pk_fma_f32 v[50:51], v[46:47], v[70:71], v[50:51]
	v_pk_fma_f32 v[52:53], v[48:49], v[72:73], v[52:53]
	v_pk_add_f32 v[50:51], v[66:67], v[50:51]
	v_pk_add_f32 v[52:53], v[68:69], v[52:53]
	v_mul_f32_e32 v54, 0x3d372713, v50
	v_mul_f32_e32 v55, 0x3d372713, v51
	v_mul_f32_e32 v54, v50, v54
	v_mul_f32_e32 v55, v51, v55
	v_mul_f32_e32 v56, 0x3d372713, v52
	v_mul_f32_e32 v57, 0x3d372713, v53
	v_fma_f32 v54, v50, v54, v50
	v_fma_f32 v55, v51, v55, v51
	v_mul_f32_e32 v56, v52, v56
	v_mul_f32_e32 v57, v53, v57
	v_mul_f32_e32 v54, 0xbfcc422a, v54
	v_mul_f32_e32 v55, 0xbfcc422a, v55
	v_fma_f32 v56, v52, v56, v52
	v_fma_f32 v57, v53, v57, v53
	v_mul_f32_e32 v54, 0x3fb8aa3b, v54
	v_mul_f32_e32 v55, 0x3fb8aa3b, v55
	v_mul_f32_e32 v56, 0xbfcc422a, v56
	v_mul_f32_e32 v57, 0xbfcc422a, v57
	v_exp_f32_e32 v54, v54
	v_exp_f32_e32 v55, v55
	v_mul_f32_e32 v56, 0x3fb8aa3b, v56
	v_mul_f32_e32 v57, 0x3fb8aa3b, v57
	v_exp_f32_e32 v56, v56
	v_exp_f32_e32 v57, v57
	v_add_f32_e32 v54, 1.0, v54
	v_add_f32_e32 v55, 1.0, v55
	v_rcp_f32_e32 v54, v54
	v_rcp_f32_e32 v55, v55
	v_add_f32_e32 v56, 1.0, v56
	v_add_f32_e32 v57, 1.0, v57
	v_rcp_f32_e32 v56, v56
	v_rcp_f32_e32 v57, v57
	v_pk_mul_f32 v[50:51], v[50:51], v[54:55]
	s_nop 0
	v_pk_mul_f32 v[42:43], v[42:43], v[50:51]
	v_pk_mul_f32 v[50:51], v[52:53], v[56:57]
	v_cvt_pk_bf16_f32 v42, v42, v43
	v_pk_mul_f32 v[44:45], v[44:45], v[50:51]
	s_nop 0
	v_cvt_pk_bf16_f32 v43, v44, v45
	global_store_dwordx2 v[130:131], v[42:43], off offset:32
	s_and_saveexec_b64 s[0:1], s[52:53]
	s_cbranch_execz .LBB0_2402
	v_mov_b64_e32 v[42:43], s[38:39]
	v_mad_i64_i32 v[42:43], s[50:51], v137, s87, v[42:43]
	v_lshl_add_u64 v[42:43], v[174:175], 2, v[42:43]
	global_store_dwordx4 v[42:43], v[46:49], off offset:64
.LBB0_2402:
	s_or_b64 exec, exec, s[0:1]
	v_mov_b32_e32 v42, 0
	v_mov_b32_e32 v43, 0
	v_mov_b32_e32 v44, 0
	v_mov_b32_e32 v45, 0
	v_mov_b32_e32 v46, 0
	v_mov_b32_e32 v47, 0
	v_mov_b32_e32 v48, 0
	v_mov_b32_e32 v49, 0
	v_mov_b32_dpp v42, v34 row_ror:1 row_mask:0xf bank_mask:0xf
	v_mov_b32_dpp v43, v35 row_ror:1 row_mask:0xf bank_mask:0xf
	v_mov_b32_dpp v44, v36 row_ror:1 row_mask:0xf bank_mask:0xf
	v_mov_b32_dpp v45, v37 row_ror:1 row_mask:0xf bank_mask:0xf
	v_mov_b32_dpp v46, v34 row_ror:2 row_mask:0xf bank_mask:0xf
	v_mov_b32_dpp v47, v35 row_ror:2 row_mask:0xf bank_mask:0xf
	v_mov_b32_dpp v48, v36 row_ror:2 row_mask:0xf bank_mask:0xf
	v_mov_b32_dpp v49, v37 row_ror:2 row_mask:0xf bank_mask:0xf
	v_cndmask_b32_e64 v42, v42, v58, s[8:9]
	v_cndmask_b32_e64 v46, v63, v46, s[10:11]
	v_cndmask_b32_e64 v43, v43, v59, s[8:9]
	v_cndmask_b32_e64 v47, v64, v47, s[10:11]
	v_cndmask_b32_e64 v44, v44, v60, s[8:9]
	v_cndmask_b32_e64 v48, v65, v48, s[10:11]
	v_cndmask_b32_e64 v45, v45, v61, s[8:9]
	v_cndmask_b32_e64 v49, v62, v49, s[10:11]
	s_and_saveexec_b64 s[0:1], s[58:59]
	s_cbranch_execz .LBB0_2404
	v_mov_b64_e32 v[42:43], s[60:61]
	v_mad_i64_i32 v[44:45], s[50:51], v144, s87, v[42:43]
	v_mad_i64_i32 v[42:43], s[50:51], v143, s87, v[42:43]
	v_lshl_add_u64 v[44:45], v[44:45], 0, v[176:177]
	v_lshl_add_u64 v[42:43], v[42:43], 0, v[176:177]
	global_load_dwordx4 v[46:49], v[44:45], off offset:64
	s_nop 0
	global_load_dwordx4 v[42:45], v[42:43], off offset:64
	s_waitcnt vmcnt(0)
.LBB0_2404:
	s_or_b64 exec, exec, s[0:1]
	v_pk_mul_f32 v[48:49], v[80:81], v[48:49]
	v_pk_mul_f32 v[46:47], v[78:79], v[46:47]
	v_pk_fma_f32 v[44:45], v[76:77], v[44:45], v[48:49]
	v_pk_fma_f32 v[42:43], v[74:75], v[42:43], v[46:47]
	v_pk_fma_f32 v[44:45], v[36:37], v[72:73], v[44:45]
	v_pk_fma_f32 v[42:43], v[34:35], v[70:71], v[42:43]
	v_pk_add_f32 v[44:45], v[68:69], v[44:45]
	v_pk_add_f32 v[42:43], v[66:67], v[42:43]
	v_mul_f32_e32 v48, 0x3d372713, v44
	v_mul_f32_e32 v46, 0x3d372713, v42
	v_mul_f32_e32 v47, 0x3d372713, v43
	v_mul_f32_e32 v49, 0x3d372713, v45
	v_mul_f32_e32 v46, v42, v46
	v_mul_f32_e32 v47, v43, v47
	v_mul_f32_e32 v48, v44, v48
	v_mul_f32_e32 v49, v45, v49
	v_fma_f32 v46, v42, v46, v42
	v_fma_f32 v47, v43, v47, v43
	v_fma_f32 v48, v44, v48, v44
	v_fma_f32 v49, v45, v49, v45
	v_mul_f32_e32 v46, 0xbfcc422a, v46
	v_mul_f32_e32 v47, 0xbfcc422a, v47
	v_mul_f32_e32 v48, 0xbfcc422a, v48
	v_mul_f32_e32 v49, 0xbfcc422a, v49
	v_mul_f32_e32 v46, 0x3fb8aa3b, v46
	v_mul_f32_e32 v47, 0x3fb8aa3b, v47
	v_mul_f32_e32 v48, 0x3fb8aa3b, v48
	v_mul_f32_e32 v49, 0x3fb8aa3b, v49
	v_exp_f32_e32 v46, v46
	v_exp_f32_e32 v47, v47
	v_exp_f32_e32 v48, v48
	v_exp_f32_e32 v49, v49
	v_add_f32_e32 v46, 1.0, v46
	v_add_f32_e32 v47, 1.0, v47
	v_add_f32_e32 v48, 1.0, v48
	v_add_f32_e32 v49, 1.0, v49
	v_rcp_f32_e32 v46, v46
	v_rcp_f32_e32 v47, v47
	v_rcp_f32_e32 v48, v48
	v_rcp_f32_e32 v49, v49
	s_and_b64 vcc, exec, s[20:21]
	v_pk_mul_f32 v[42:43], v[42:43], v[46:47]
	s_mov_b64 s[0:1], -1
	v_pk_mul_f32 v[44:45], v[44:45], v[48:49]
	v_pk_mul_f32 v[42:43], v[38:39], v[42:43]
	v_pk_mul_f32 v[44:45], v[40:41], v[44:45]
	v_cvt_pk_bf16_f32 v42, v42, v43
	v_cvt_pk_bf16_f32 v43, v44, v45
	global_store_dwordx2 v[122:123], v[42:43], off offset:32
	s_cbranch_vccnz .LBB0_2413
	v_cmp_lt_u32_e32 vcc, s88, v145
	s_and_saveexec_b64 s[0:1], vcc
	s_cbranch_execz .LBB0_2407
	v_add_u32_e32 v42, s91, v145
	v_mul_hi_i32_i24_e32 v43, 0x2c00, v42
	v_mul_i32_i24_e32 v42, 0x2c00, v42
	v_lshl_add_u64 v[42:43], s[40:41], 0, v[42:43]
	v_lshl_add_u64 v[42:43], v[174:175], 2, v[42:43]
	global_store_dwordx4 v[42:43], v[34:37], off offset:64

.LBB0_2435:
	v_mov_b32_e32 v34, 0
	v_mov_b32_e32 v35, 0
	v_mov_b32_e32 v36, 0
	v_mov_b32_e32 v37, 0
	v_mov_b32_e32 v39, 0
	v_mov_b32_e32 v40, 0
	v_mov_b32_e32 v41, 0
	v_mov_b32_e32 v38, 0
	v_mov_b32_dpp v34, v22 row_ror:1 row_mask:0xf bank_mask:0xf
	v_mov_b32_dpp v35, v23 row_ror:1 row_mask:0xf bank_mask:0xf
	v_mov_b32_dpp v36, v24 row_ror:1 row_mask:0xf bank_mask:0xf
	v_mov_b32_dpp v37, v25 row_ror:1 row_mask:0xf bank_mask:0xf
	v_mov_b32_dpp v39, v22 row_ror:2 row_mask:0xf bank_mask:0xf
	v_mov_b32_dpp v40, v23 row_ror:2 row_mask:0xf bank_mask:0xf
	v_mov_b32_dpp v41, v24 row_ror:2 row_mask:0xf bank_mask:0xf
	v_mov_b32_dpp v38, v25 row_ror:2 row_mask:0xf bank_mask:0xf
	v_cndmask_b32_e64 v26, v34, v50, s[8:9]
	v_cndmask_b32_e64 v30, v55, v39, s[10:11]
	v_cndmask_b32_e64 v27, v35, v51, s[8:9]
	v_cndmask_b32_e64 v31, v56, v40, s[10:11]
	v_cndmask_b32_e64 v28, v36, v52, s[8:9]
	v_cndmask_b32_e64 v32, v57, v41, s[10:11]
	v_cndmask_b32_e64 v29, v37, v53, s[8:9]
	v_cndmask_b32_e64 v33, v54, v38, s[10:11]
	s_and_saveexec_b64 s[0:1], s[54:55]
	s_cbranch_execz .LBB0_2437
	v_mov_b64_e32 v[26:27], s[60:61]
	v_mad_i64_i32 v[28:29], s[22:23], v108, s87, v[26:27]
	v_mad_i64_i32 v[26:27], s[22:23], v107, s87, v[26:27]
	v_lshl_add_u64 v[28:29], v[28:29], 0, v[176:177]
	v_lshl_add_u64 v[26:27], v[26:27], 0, v[176:177]
	global_load_dwordx4 v[30:33], v[28:29], off offset:64
	s_nop 0
	global_load_dwordx4 v[26:29], v[26:27], off offset:64
	s_waitcnt vmcnt(0)
.LBB0_2437:
	s_or_b64 exec, exec, s[0:1]
	v_pk_mul_f32 v[30:31], v[78:79], v[30:31]
	v_pk_mul_f32 v[32:33], v[80:81], v[32:33]
	v_pk_fma_f32 v[26:27], v[74:75], v[26:27], v[30:31]
	v_pk_fma_f32 v[28:29], v[76:77], v[28:29], v[32:33]
	v_pk_fma_f32 v[26:27], v[22:23], v[70:71], v[26:27]
	v_pk_fma_f32 v[28:29], v[24:25], v[72:73], v[28:29]
	v_pk_add_f32 v[26:27], v[66:67], v[26:27]
	v_pk_add_f32 v[28:29], v[68:69], v[28:29]
	v_mul_f32_e32 v30, 0x3d372713, v26
	v_mul_f32_e32 v31, 0x3d372713, v27
	v_mul_f32_e32 v30, v26, v30
	v_mul_f32_e32 v31, v27, v31
	v_mul_f32_e32 v32, 0x3d372713, v28
	v_mul_f32_e32 v33, 0x3d372713, v29
	v_fma_f32 v30, v26, v30, v26
	v_fma_f32 v31, v27, v31, v27
	v_mul_f32_e32 v32, v28, v32
	v_mul_f32_e32 v33, v29, v33
	v_mul_f32_e32 v30, 0xbfcc422a, v30
	v_mul_f32_e32 v31, 0xbfcc422a, v31
	v_fma_f32 v32, v28, v32, v28
	v_fma_f32 v33, v29, v33, v29
	v_mul_f32_e32 v30, 0x3fb8aa3b, v30
	v_mul_f32_e32 v31, 0x3fb8aa3b, v31
	v_mul_f32_e32 v32, 0xbfcc422a, v32
	v_mul_f32_e32 v33, 0xbfcc422a, v33
	v_exp_f32_e32 v30, v30
	v_exp_f32_e32 v31, v31
	v_mul_f32_e32 v32, 0x3fb8aa3b, v32
	v_mul_f32_e32 v33, 0x3fb8aa3b, v33
	v_exp_f32_e32 v32, v32
	v_exp_f32_e32 v33, v33
	v_add_f32_e32 v30, 1.0, v30
	v_add_f32_e32 v31, 1.0, v31
	v_rcp_f32_e32 v30, v30
	v_rcp_f32_e32 v31, v31
	v_add_f32_e32 v32, 1.0, v32
	v_add_f32_e32 v33, 1.0, v33
	v_rcp_f32_e32 v32, v32
	v_rcp_f32_e32 v33, v33
	v_pk_mul_f32 v[26:27], v[26:27], v[30:31]
	s_nop 0
	v_pk_mul_f32 v[18:19], v[18:19], v[26:27]
	v_pk_mul_f32 v[26:27], v[28:29], v[32:33]
	v_cvt_pk_bf16_f32 v18, v18, v19
	v_pk_mul_f32 v[20:21], v[20:21], v[26:27]
	s_nop 0
	v_cvt_pk_bf16_f32 v19, v20, v21
	global_store_dwordx2 v[90:91], v[18:19], off offset:32
	s_and_saveexec_b64 s[0:1], s[54:55]
	s_cbranch_execz .LBB0_2439
	v_mov_b64_e32 v[18:19], s[38:39]
	v_mad_i64_i32 v[18:19], s[22:23], v109, s87, v[18:19]
	v_lshl_add_u64 v[18:19], v[174:175], 2, v[18:19]
	global_store_dwordx4 v[18:19], v[22:25], off offset:64
.LBB0_2439:
	s_or_b64 exec, exec, s[0:1]
	v_mov_b32_e32 v26, 0
	v_mov_b32_e32 v27, 0
	v_mov_b32_e32 v28, 0
	v_mov_b32_e32 v29, 0
	v_mov_b32_e32 v31, 0
	v_mov_b32_e32 v32, 0
	v_mov_b32_e32 v33, 0
	v_mov_b32_e32 v30, 0
	v_mov_b32_dpp v26, v14 row_ror:1 row_mask:0xf bank_mask:0xf
	v_mov_b32_dpp v27, v15 row_ror:1 row_mask:0xf bank_mask:0xf
	v_mov_b32_dpp v28, v16 row_ror:1 row_mask:0xf bank_mask:0xf
	v_mov_b32_dpp v29, v17 row_ror:1 row_mask:0xf bank_mask:0xf
	v_mov_b32_dpp v31, v14 row_ror:2 row_mask:0xf bank_mask:0xf
	v_mov_b32_dpp v32, v15 row_ror:2 row_mask:0xf bank_mask:0xf
	v_mov_b32_dpp v33, v16 row_ror:2 row_mask:0xf bank_mask:0xf
	v_mov_b32_dpp v30, v17 row_ror:2 row_mask:0xf bank_mask:0xf
	v_cndmask_b32_e64 v18, v26, v34, s[8:9]
	v_cndmask_b32_e64 v22, v39, v31, s[10:11]
	v_cndmask_b32_e64 v19, v27, v35, s[8:9]
	v_cndmask_b32_e64 v23, v40, v32, s[10:11]
	v_cndmask_b32_e64 v20, v28, v36, s[8:9]
	v_cndmask_b32_e64 v24, v41, v33, s[10:11]
	v_cndmask_b32_e64 v21, v29, v37, s[8:9]
	v_cndmask_b32_e64 v25, v38, v30, s[10:11]
	s_and_saveexec_b64 s[0:1], s[56:57]
	s_cbranch_execz .LBB0_2441
	v_mov_b64_e32 v[18:19], s[60:61]
	v_mad_i64_i32 v[20:21], s[22:23], v125, s87, v[18:19]
	v_mad_i64_i32 v[18:19], s[22:23], v124, s87, v[18:19]
	v_lshl_add_u64 v[20:21], v[20:21], 0, v[176:177]
	v_lshl_add_u64 v[18:19], v[18:19], 0, v[176:177]
	global_load_dwordx4 v[22:25], v[20:21], off offset:64
	s_nop 0
	global_load_dwordx4 v[18:21], v[18:19], off offset:64
	s_waitcnt vmcnt(0)
.LBB0_2441:
	s_or_b64 exec, exec, s[0:1]
	v_pk_mul_f32 v[22:23], v[78:79], v[22:23]
	v_pk_mul_f32 v[24:25], v[80:81], v[24:25]
	v_pk_fma_f32 v[18:19], v[74:75], v[18:19], v[22:23]
	v_pk_fma_f32 v[20:21], v[76:77], v[20:21], v[24:25]
	v_pk_fma_f32 v[18:19], v[14:15], v[70:71], v[18:19]
	v_pk_fma_f32 v[20:21], v[16:17], v[72:73], v[20:21]
	v_pk_add_f32 v[18:19], v[66:67], v[18:19]
	v_pk_add_f32 v[20:21], v[68:69], v[20:21]
	v_mul_f32_e32 v22, 0x3d372713, v18
	v_mul_f32_e32 v23, 0x3d372713, v19
	v_mul_f32_e32 v22, v18, v22
	v_mul_f32_e32 v23, v19, v23
	v_mul_f32_e32 v24, 0x3d372713, v20
	v_mul_f32_e32 v25, 0x3d372713, v21
	v_fma_f32 v22, v18, v22, v18
	v_fma_f32 v23, v19, v23, v19
	v_mul_f32_e32 v24, v20, v24
	v_mul_f32_e32 v25, v21, v25
	v_mul_f32_e32 v22, 0xbfcc422a, v22
	v_mul_f32_e32 v23, 0xbfcc422a, v23
	v_fma_f32 v24, v20, v24, v20
	v_fma_f32 v25, v21, v25, v21
	v_mul_f32_e32 v22, 0x3fb8aa3b, v22
	v_mul_f32_e32 v23, 0x3fb8aa3b, v23
	v_mul_f32_e32 v24, 0xbfcc422a, v24
	v_mul_f32_e32 v25, 0xbfcc422a, v25
	v_exp_f32_e32 v22, v22
	v_exp_f32_e32 v23, v23
	v_mul_f32_e32 v24, 0x3fb8aa3b, v24
	v_mul_f32_e32 v25, 0x3fb8aa3b, v25
	v_exp_f32_e32 v24, v24
	v_exp_f32_e32 v25, v25
	v_add_f32_e32 v22, 1.0, v22
	v_add_f32_e32 v23, 1.0, v23
	v_rcp_f32_e32 v22, v22
	v_rcp_f32_e32 v23, v23
	v_add_f32_e32 v24, 1.0, v24
	v_add_f32_e32 v25, 1.0, v25
	v_rcp_f32_e32 v24, v24
	v_rcp_f32_e32 v25, v25
	v_pk_mul_f32 v[18:19], v[18:19], v[22:23]
	s_nop 0
	v_pk_mul_f32 v[10:11], v[10:11], v[18:19]
	v_pk_mul_f32 v[18:19], v[20:21], v[24:25]
	v_cvt_pk_bf16_f32 v10, v10, v11
	v_pk_mul_f32 v[12:13], v[12:13], v[18:19]
	s_nop 0
	v_cvt_pk_bf16_f32 v11, v12, v13
	global_store_dwordx2 v[92:93], v[10:11], off offset:32
	s_and_saveexec_b64 s[0:1], s[56:57]
	s_cbranch_execz .LBB0_2443
	v_mov_b64_e32 v[10:11], s[38:39]
	v_mad_i64_i32 v[10:11], s[22:23], v126, s87, v[10:11]
	v_lshl_add_u64 v[10:11], v[174:175], 2, v[10:11]
	global_store_dwordx4 v[10:11], v[14:17], off offset:64
.LBB0_2443:
	s_or_b64 exec, exec, s[0:1]
	v_mov_b32_e32 v10, 0
	v_mov_b32_e32 v11, 0
	v_mov_b32_e32 v12, 0
	v_mov_b32_e32 v13, 0
	v_mov_b32_e32 v14, 0
	v_mov_b32_e32 v15, 0
	v_mov_b32_e32 v16, 0
	v_mov_b32_e32 v17, 0
	v_mov_b32_dpp v10, v2 row_ror:1 row_mask:0xf bank_mask:0xf
	v_mov_b32_dpp v11, v3 row_ror:1 row_mask:0xf bank_mask:0xf
	v_mov_b32_dpp v12, v4 row_ror:1 row_mask:0xf bank_mask:0xf
	v_mov_b32_dpp v13, v5 row_ror:1 row_mask:0xf bank_mask:0xf
	v_mov_b32_dpp v14, v2 row_ror:2 row_mask:0xf bank_mask:0xf
	v_mov_b32_dpp v15, v3 row_ror:2 row_mask:0xf bank_mask:0xf
	v_mov_b32_dpp v16, v4 row_ror:2 row_mask:0xf bank_mask:0xf
	v_mov_b32_dpp v17, v5 row_ror:2 row_mask:0xf bank_mask:0xf
	v_cndmask_b32_e64 v10, v10, v26, s[8:9]
	v_cndmask_b32_e64 v14, v31, v14, s[10:11]
	v_cndmask_b32_e64 v11, v11, v27, s[8:9]
	v_cndmask_b32_e64 v15, v32, v15, s[10:11]
	v_cndmask_b32_e64 v12, v12, v28, s[8:9]
	v_cndmask_b32_e64 v16, v33, v16, s[10:11]
	v_cndmask_b32_e64 v13, v13, v29, s[8:9]
	v_cndmask_b32_e64 v17, v30, v17, s[10:11]
	s_and_saveexec_b64 s[0:1], s[62:63]
	s_cbranch_execz .LBB0_2445
	v_mov_b64_e32 v[10:11], s[60:61]
	v_mad_i64_i32 v[12:13], s[22:23], v128, s87, v[10:11]
	v_mad_i64_i32 v[10:11], s[22:23], v127, s87, v[10:11]
	v_lshl_add_u64 v[12:13], v[12:13], 0, v[176:177]
	v_lshl_add_u64 v[10:11], v[10:11], 0, v[176:177]
	global_load_dwordx4 v[14:17], v[12:13], off offset:64
	s_nop 0
	global_load_dwordx4 v[10:13], v[10:11], off offset:64
	s_waitcnt vmcnt(0)
.LBB0_2445:
	s_or_b64 exec, exec, s[0:1]
	v_pk_mul_f32 v[16:17], v[80:81], v[16:17]
	v_pk_mul_f32 v[14:15], v[78:79], v[14:15]
	v_pk_fma_f32 v[12:13], v[76:77], v[12:13], v[16:17]
	v_pk_fma_f32 v[10:11], v[74:75], v[10:11], v[14:15]
	v_pk_fma_f32 v[12:13], v[4:5], v[72:73], v[12:13]
	v_pk_fma_f32 v[10:11], v[2:3], v[70:71], v[10:11]
	v_pk_add_f32 v[12:13], v[68:69], v[12:13]
	v_pk_add_f32 v[10:11], v[66:67], v[10:11]
	v_mul_f32_e32 v16, 0x3d372713, v12
	v_mul_f32_e32 v14, 0x3d372713, v10
	v_mul_f32_e32 v15, 0x3d372713, v11
	v_mul_f32_e32 v17, 0x3d372713, v13
	v_mul_f32_e32 v14, v10, v14
	v_mul_f32_e32 v15, v11, v15
	v_mul_f32_e32 v16, v12, v16
	v_mul_f32_e32 v17, v13, v17
	v_fma_f32 v14, v10, v14, v10
	v_fma_f32 v15, v11, v15, v11
	v_fma_f32 v16, v12, v16, v12
	v_fma_f32 v17, v13, v17, v13
	v_mul_f32_e32 v14, 0xbfcc422a, v14
	v_mul_f32_e32 v15, 0xbfcc422a, v15
	v_mul_f32_e32 v16, 0xbfcc422a, v16
	v_mul_f32_e32 v17, 0xbfcc422a, v17
	v_mul_f32_e32 v14, 0x3fb8aa3b, v14
	v_mul_f32_e32 v15, 0x3fb8aa3b, v15
	v_mul_f32_e32 v16, 0x3fb8aa3b, v16
	v_mul_f32_e32 v17, 0x3fb8aa3b, v17
	v_exp_f32_e32 v14, v14
	v_exp_f32_e32 v15, v15
	v_exp_f32_e32 v16, v16
	v_exp_f32_e32 v17, v17
	v_add_f32_e32 v14, 1.0, v14
	v_add_f32_e32 v15, 1.0, v15
	v_add_f32_e32 v16, 1.0, v16
	v_add_f32_e32 v17, 1.0, v17
	v_rcp_f32_e32 v14, v14
	v_rcp_f32_e32 v15, v15
	v_rcp_f32_e32 v16, v16
	v_rcp_f32_e32 v17, v17
	s_and_b64 vcc, exec, s[20:21]
	v_pk_mul_f32 v[10:11], v[10:11], v[14:15]
	s_mov_b64 s[0:1], -1
	v_pk_mul_f32 v[12:13], v[12:13], v[16:17]
	v_pk_mul_f32 v[10:11], v[6:7], v[10:11]
	v_pk_mul_f32 v[12:13], v[8:9], v[12:13]
	v_cvt_pk_bf16_f32 v10, v10, v11
	v_cvt_pk_bf16_f32 v11, v12, v13
	global_store_dwordx2 v[94:95], v[10:11], off offset:32
	s_cbranch_vccnz .LBB0_2455
	v_cmp_lt_u32_e32 vcc, s88, v110
	s_and_saveexec_b64 s[0:1], vcc
	s_cbranch_execz .LBB0_2448
	v_add_u32_e32 v10, s92, v110
	v_mul_hi_i32_i24_e32 v11, 0x2c00, v10
	v_mul_i32_i24_e32 v10, 0x2c00, v10
	v_lshl_add_u64 v[10:11], s[40:41], 0, v[10:11]
	v_lshl_add_u64 v[10:11], v[174:175], 2, v[10:11]
	global_store_dwordx4 v[10:11], v[2:5], off offset:64
